# pass C: 16 hgrn_norm_w loads batched up front (was a serialized load/wait chain)
# baseline (speedup 1.0000x reference)
.LBB0_643:
	v_mul_f32_e32 v76, v51, v51
	v_fmac_f32_e32 v76, v50, v50
	v_fmac_f32_e32 v76, v52, v52
	v_fmac_f32_e32 v76, v53, v53
	v_fmac_f32_e32 v76, v54, v54
	v_fmac_f32_e32 v76, v55, v55
	v_fmac_f32_e32 v76, v56, v56
	v_fmac_f32_e32 v76, v57, v57
	v_fmac_f32_e32 v76, v58, v58
	v_fmac_f32_e32 v76, v59, v59
	v_fmac_f32_e32 v76, v60, v60
	v_fmac_f32_e32 v76, v61, v61
	v_fmac_f32_e32 v76, v62, v62
	v_fmac_f32_e32 v76, v63, v63
	v_fmac_f32_e32 v76, v64, v64
	v_fmac_f32_e32 v76, v65, v65
	v_fmac_f32_e32 v76, v34, v34
	v_fmac_f32_e32 v76, v35, v35
	v_fmac_f32_e32 v76, v36, v36
	v_fmac_f32_e32 v76, v37, v37
	v_fmac_f32_e32 v76, v38, v38
	v_fmac_f32_e32 v76, v39, v39
	v_fmac_f32_e32 v76, v40, v40
	v_fmac_f32_e32 v76, v41, v41
	v_fmac_f32_e32 v76, v42, v42
	v_fmac_f32_e32 v76, v43, v43
	v_fmac_f32_e32 v76, v44, v44
	v_fmac_f32_e32 v76, v45, v45
	v_fmac_f32_e32 v76, v46, v46
	v_fmac_f32_e32 v76, v47, v47
	v_fmac_f32_e32 v76, v48, v48
	v_fmac_f32_e32 v76, v49, v49
	v_fmac_f32_e32 v76, v18, v18
	v_fmac_f32_e32 v76, v19, v19
	v_fmac_f32_e32 v76, v20, v20
	v_fmac_f32_e32 v76, v21, v21
	v_fmac_f32_e32 v76, v22, v22
	v_fmac_f32_e32 v76, v23, v23
	v_fmac_f32_e32 v76, v24, v24
	v_fmac_f32_e32 v76, v25, v25
	v_fmac_f32_e32 v76, v26, v26
	v_fmac_f32_e32 v76, v27, v27
	v_fmac_f32_e32 v76, v28, v28
	v_fmac_f32_e32 v76, v29, v29
	v_fmac_f32_e32 v76, v30, v30
	v_fmac_f32_e32 v76, v31, v31
	v_fmac_f32_e32 v76, v32, v32
	v_fmac_f32_e32 v76, v33, v33
	v_fmac_f32_e32 v76, v2, v2
	v_fmac_f32_e32 v76, v3, v3
	v_fmac_f32_e32 v76, v4, v4
	v_fmac_f32_e32 v76, v5, v5
	v_fmac_f32_e32 v76, v6, v6
	v_fmac_f32_e32 v76, v7, v7
	v_pk_mul_f32 v[74:75], v[8:9], v[8:9]
	v_pk_mul_f32 v[72:73], v[10:11], v[10:11]
	v_add_f32_e32 v74, v74, v76
	v_add_f32_e32 v74, v75, v74
	v_add_f32_e32 v72, v72, v74
	v_pk_mul_f32 v[70:71], v[12:13], v[12:13]
	v_add_f32_e32 v72, v73, v72
	v_add_f32_e32 v70, v70, v72
	v_pk_mul_f32 v[68:69], v[14:15], v[14:15]
	v_add_f32_e32 v70, v71, v70
	v_add_f32_e32 v68, v68, v70
	v_pk_mul_f32 v[66:67], v[16:17], v[16:17]
	v_add_f32_e32 v68, v69, v68
	v_add_f32_e32 v66, v66, v68
	v_add_f32_e32 v66, v67, v66
	ds_bpermute_b32 v67, v212, v66
	s_xor_b64 s[54:55], s[4:5], -1
	s_lshl_b32 s4, s59, 5
	s_or_b32 s68, s4, s16
	s_ashr_i32 s69, s68, 31
	s_mul_i32 s5, s68, 0x2880
	v_readlane_b32 s6, v246, 36
	s_waitcnt lgkmcnt(0)
	v_add_f32_e32 v66, v66, v67
	s_mul_hi_i32 s4, s68, 0x2880
	v_readlane_b32 s7, v246, 37
	s_add_u32 s5, s6, s5
	v_fmamk_f32 v66, v66, 0x3c000000, v216
	s_addc_u32 s6, s7, s4
	v_cmp_gt_f32_e32 vcc, s36, v66
	v_mul_f32_e32 v67, 0x4b800000, v66
	s_add_u32 s4, s5, s58
	v_cndmask_b32_e32 v66, v66, v67, vcc
	s_addc_u32 s5, s6, 0
	v_rsq_f32_e32 v78, v66
	v_lshl_add_u64 v[66:67], s[4:5], 0, v[0:1]
	s_mov_b64 s[4:5], 0x1800
	v_lshl_add_u64 v[76:77], v[66:67], 0, s[4:5]
	v_mov_b32_e32 v179, v1
	v_lshl_add_u64 v[66:67], v[76:77], 0, v[178:179]
	global_load_dwordx4 v[100:103], v[66:67], off nt
	v_mov_b32_e32 v181, v1
	v_lshl_add_u64 v[70:71], v[76:77], 0, v[180:181]
	global_load_dwordx4 v[104:107], v[70:71], off nt
	v_add_co_u32_e64 v66, s[4:5], s37, v70
	v_mov_b32_e32 v183, v1
	v_mov_b32_e32 v185, v1
	v_addc_co_u32_e64 v67, s[4:5], 0, v71, s[4:5]
	global_load_dwordx4 v[108:111], v[66:67], off offset:512 nt
	s_mov_b32 s4, 0x14000
	v_add_co_u32_e64 v66, s[4:5], s4, v70
	v_mov_b32_e32 v187, v1
	v_mov_b32_e32 v189, v1
	v_addc_co_u32_e64 v67, s[4:5], 0, v71, s[4:5]
	global_load_dwordx4 v[112:115], v[66:67], off offset:1024 nt
	v_lshl_add_u64 v[68:69], v[76:77], 0, v[182:183]
	global_load_dwordx4 v[116:119], v[68:69], off nt
	v_lshl_add_u64 v[68:69], v[76:77], 0, v[184:185]
	global_load_dwordx4 v[120:123], v[68:69], off nt
	v_lshl_add_u64 v[68:69], v[76:77], 0, v[186:187]
	global_load_dwordx4 v[124:127], v[68:69], off nt
	v_lshl_add_u64 v[68:69], v[76:77], 0, v[188:189]
	global_load_dwordx4 v[128:131], v[68:69], off nt
	global_load_dwordx4 v[132:135], v[176:177], off
	global_load_dwordx4 v[136:139], v[176:177], off offset:32
	global_load_dwordx4 v[140:143], v[176:177], off offset:64
	global_load_dwordx4 v[144:147], v[176:177], off offset:96
	global_load_dwordx4 v[148:151], v[176:177], off offset:128
	global_load_dwordx4 v[156:159], v[176:177], off offset:160
	global_load_dwordx4 v[160:163], v[176:177], off offset:192
	global_load_dwordx4 v[164:167], v[176:177], off offset:224
	global_load_dwordx4 v[168:171], v[176:177], off offset:256
	global_load_dwordx4 v[84:87], v[176:177], off offset:288
	global_load_dwordx4 v[88:91], v[176:177], off offset:320
	global_load_dwordx4 v[92:95], v[176:177], off offset:352
	global_load_dwordx4 v[96:99], v[176:177], off offset:384
	v_add_u32_e32 v82, v208, v207
	v_mul_f32_e32 v79, 0x45800000, v78
	v_mov_b32_e32 v191, v1
	v_mov_b32_e32 v193, v1
	v_mov_b32_e32 v195, v1
	v_mov_b32_e32 v197, v1
	v_mov_b32_e32 v199, v1
	v_mov_b32_e32 v201, v1
	v_mov_b32_e32 v203, v1
	v_mov_b32_e32 v205, v1
	s_mov_b32 s59, 1
	v_add_u32_e32 v67, 0x840, v229
	v_cndmask_b32_e32 v66, v78, v79, vcc
	v_pk_mul_f32 v[50:51], v[50:51], v[66:67] op_sel_hi:[1,0]
	v_pk_mul_f32 v[52:53], v[52:53], v[66:67] op_sel_hi:[1,0]
	v_pk_mul_f32 v[54:55], v[54:55], v[66:67] op_sel_hi:[1,0]
	v_pk_mul_f32 v[56:57], v[56:57], v[66:67] op_sel_hi:[1,0]
	v_pk_mul_f32 v[58:59], v[58:59], v[66:67] op_sel_hi:[1,0]
	v_pk_mul_f32 v[34:35], v[34:35], v[66:67] op_sel_hi:[1,0]
	v_pk_mul_f32 v[36:37], v[36:37], v[66:67] op_sel_hi:[1,0]
	v_pk_mul_f32 v[38:39], v[38:39], v[66:67] op_sel_hi:[1,0]
	v_pk_mul_f32 v[40:41], v[40:41], v[66:67] op_sel_hi:[1,0]
	v_pk_mul_f32 v[42:43], v[42:43], v[66:67] op_sel_hi:[1,0]
	v_pk_mul_f32 v[18:19], v[18:19], v[66:67] op_sel_hi:[1,0]
	v_pk_mul_f32 v[20:21], v[20:21], v[66:67] op_sel_hi:[1,0]
	v_pk_mul_f32 v[22:23], v[22:23], v[66:67] op_sel_hi:[1,0]
	v_pk_mul_f32 v[24:25], v[24:25], v[66:67] op_sel_hi:[1,0]
	v_pk_mul_f32 v[26:27], v[26:27], v[66:67] op_sel_hi:[1,0]
	v_pk_mul_f32 v[2:3], v[2:3], v[66:67] op_sel_hi:[1,0]
	v_pk_mul_f32 v[4:5], v[4:5], v[66:67] op_sel_hi:[1,0]
	v_pk_mul_f32 v[6:7], v[6:7], v[66:67] op_sel_hi:[1,0]
	v_pk_mul_f32 v[8:9], v[8:9], v[66:67] op_sel_hi:[1,0]
	v_pk_mul_f32 v[10:11], v[10:11], v[66:67] op_sel_hi:[1,0]
	s_lshl_b64 s[4:5], s[68:69], 12
	s_mov_b64 s[68:69], -1
	s_andn2_b64 vcc, exec, s[54:55]
	v_add_u32_e32 v68, 0xc60, v229
	v_add_u32_e32 v69, 0x18c0, v229
	v_add_u32_e32 v70, 0x1080, v229
	v_add_u32_e32 v71, 0x14a0, v229
	s_waitcnt vmcnt(20)
	ds_write2_b64 v228, v[100:101], v[102:103] offset1:1
	s_waitcnt vmcnt(19)
	ds_write2_b64 v229, v[104:105], v[106:107] offset1:1
	s_waitcnt vmcnt(18)
	ds_write2_b64 v229, v[108:109], v[110:111] offset0:132 offset1:133
	s_waitcnt vmcnt(17)
	ds_write2_b64 v67, v[112:113], v[114:115] offset1:1
	s_waitcnt vmcnt(16)
	ds_write2_b64 v68, v[116:117], v[118:119] offset1:1
	s_waitcnt vmcnt(15)
	ds_write2_b64 v70, v[120:121], v[122:123] offset1:1
	s_waitcnt vmcnt(14)
	ds_write2_b64 v71, v[124:125], v[126:127] offset1:1
	s_waitcnt vmcnt(13)
	ds_write2_b64 v69, v[128:129], v[130:131] offset1:1
	global_load_dwordx4 v[100:103], v[176:177], off offset:416
	global_load_dwordx4 v[104:107], v[176:177], off offset:448
	global_load_dwordx4 v[108:111], v[176:177], off offset:480
	ds_read_b64 v[76:77], v82
	s_waitcnt lgkmcnt(0)
	v_lshlrev_b32_e32 v78, 16, v76
	v_and_b32_e32 v79, 0xffff0000, v76
	v_mul_f32_e32 v76, 0xbfb8aa3b, v78
	v_exp_f32_e32 v76, v76
	s_waitcnt vmcnt(15)
	v_mov_b64_e32 v[72:73], v[132:133]
	v_mov_b64_e32 v[74:75], v[134:135]
	v_pk_mul_f32 v[50:51], v[72:73], v[50:51]
	v_mul_f32_e32 v72, 0xbfb8aa3b, v79
	v_exp_f32_e32 v72, v72
	v_add_f32_e32 v76, 1.0, v76
	v_rcp_f32_e32 v80, v76
	v_pk_mul_f32 v[52:53], v[74:75], v[52:53]
	v_add_f32_e32 v72, 1.0, v72
	v_rcp_f32_e32 v81, v72
	s_nop 0
	v_pk_mul_f32 v[72:73], v[80:81], v[78:79]
	s_nop 0
	v_pk_mul_f32 v[50:51], v[72:73], v[50:51]
	v_lshlrev_b32_e32 v72, 16, v77
	v_and_b32_e32 v73, 0xffff0000, v77
	v_mul_f32_e32 v76, 0xbfb8aa3b, v72
	v_mul_f32_e32 v74, 0xbfb8aa3b, v73
	v_exp_f32_e32 v76, v76
	v_exp_f32_e32 v74, v74
	v_cvt_pk_bf16_f32 v50, v50, v51
	v_add_u32_e32 v78, v208, v227
	v_add_f32_e32 v76, 1.0, v76
	v_add_f32_e32 v74, 1.0, v74
	v_rcp_f32_e32 v76, v76
	v_rcp_f32_e32 v77, v74
	s_nop 0
	v_pk_mul_f32 v[72:73], v[76:77], v[72:73]
	s_nop 0
	v_pk_mul_f32 v[52:53], v[72:73], v[52:53]
	v_cvt_pk_bf16_f32 v51, v52, v53
	ds_write_b64 v82, v[50:51]
	ds_read_b64 v[50:51], v78
	s_waitcnt lgkmcnt(0)
	v_lshlrev_b32_e32 v52, 16, v50
	v_and_b32_e32 v53, 0xffff0000, v50
	v_mul_f32_e32 v50, 0xbfb8aa3b, v52
	v_exp_f32_e32 v50, v50
	s_waitcnt vmcnt(14)
	v_mov_b64_e32 v[72:73], v[136:137]
	v_mov_b64_e32 v[74:75], v[138:139]
	v_pk_mul_f32 v[54:55], v[72:73], v[54:55]
	v_add_f32_e32 v50, 1.0, v50
	v_rcp_f32_e32 v76, v50
	v_mul_f32_e32 v50, 0xbfb8aa3b, v53
	v_exp_f32_e32 v50, v50
	v_pk_mul_f32 v[56:57], v[74:75], v[56:57]
	v_add_f32_e32 v50, 1.0, v50
	v_rcp_f32_e32 v77, v50
	v_lshlrev_b32_e32 v50, 16, v51
	v_and_b32_e32 v51, 0xffff0000, v51
	v_pk_mul_f32 v[52:53], v[76:77], v[52:53]
	s_nop 0
	v_pk_mul_f32 v[52:53], v[52:53], v[54:55]
	v_mul_f32_e32 v54, 0xbfb8aa3b, v50
	v_mul_f32_e32 v55, 0xbfb8aa3b, v51
	v_exp_f32_e32 v54, v54
	v_exp_f32_e32 v55, v55
	v_cvt_pk_bf16_f32 v52, v52, v53
	v_add_f32_e32 v54, 1.0, v54
	v_add_f32_e32 v55, 1.0, v55
	v_rcp_f32_e32 v54, v54
	v_rcp_f32_e32 v55, v55
	s_nop 0
	v_pk_mul_f32 v[50:51], v[54:55], v[50:51]
	s_nop 0
	v_pk_mul_f32 v[50:51], v[50:51], v[56:57]
	s_nop 0
	v_cvt_pk_bf16_f32 v53, v50, v51
	ds_write_b64 v78, v[52:53]
	ds_read_b64 v[50:51], v230
	s_waitcnt lgkmcnt(0)
	v_lshlrev_b32_e32 v56, 16, v50
	v_and_b32_e32 v57, 0xffff0000, v50
	v_mul_f32_e32 v50, 0xbfb8aa3b, v56
	v_exp_f32_e32 v50, v50
	s_waitcnt vmcnt(13)
	v_mov_b64_e32 v[52:53], v[140:141]
	v_mov_b64_e32 v[54:55], v[142:143]
	v_pk_mul_f32 v[52:53], v[52:53], v[58:59]
	v_add_f32_e32 v50, 1.0, v50
	v_rcp_f32_e32 v72, v50
	v_mul_f32_e32 v50, 0xbfb8aa3b, v57
	v_exp_f32_e32 v50, v50
	v_pk_mul_f32 v[58:59], v[60:61], v[66:67] op_sel_hi:[1,0]
	v_pk_mul_f32 v[60:61], v[62:63], v[66:67] op_sel_hi:[1,0]
	v_pk_mul_f32 v[54:55], v[54:55], v[58:59]
	v_add_f32_e32 v50, 1.0, v50
	v_rcp_f32_e32 v73, v50
	v_lshlrev_b32_e32 v50, 16, v51
	v_and_b32_e32 v51, 0xffff0000, v51
	v_pk_mul_f32 v[56:57], v[72:73], v[56:57]
	s_nop 0
	v_pk_mul_f32 v[52:53], v[56:57], v[52:53]
	v_mul_f32_e32 v56, 0xbfb8aa3b, v50
	v_mul_f32_e32 v57, 0xbfb8aa3b, v51
	v_exp_f32_e32 v56, v56
	v_exp_f32_e32 v57, v57
	v_cvt_pk_bf16_f32 v52, v52, v53
	v_add_f32_e32 v56, 1.0, v56
	v_add_f32_e32 v57, 1.0, v57
	v_rcp_f32_e32 v56, v56
	v_rcp_f32_e32 v57, v57
	s_nop 0
	v_pk_mul_f32 v[50:51], v[56:57], v[50:51]
	s_nop 0
	v_pk_mul_f32 v[50:51], v[50:51], v[54:55]
	ds_read_b64 v[54:55], v231
	v_cvt_pk_bf16_f32 v53, v50, v51
	ds_write_b64 v230, v[52:53]
	s_waitcnt lgkmcnt(1)
	v_lshlrev_b32_e32 v56, 16, v54
	v_and_b32_e32 v57, 0xffff0000, v54
	v_mul_f32_e32 v54, 0xbfb8aa3b, v56
	v_exp_f32_e32 v54, v54
	s_waitcnt vmcnt(12)
	v_mov_b64_e32 v[50:51], v[144:145]
	v_mov_b64_e32 v[52:53], v[146:147]
	v_pk_mul_f32 v[50:51], v[50:51], v[60:61]
	v_add_f32_e32 v54, 1.0, v54
	v_rcp_f32_e32 v58, v54
	v_mul_f32_e32 v54, 0xbfb8aa3b, v57
	v_exp_f32_e32 v54, v54
	s_nop 0
	v_add_f32_e32 v54, 1.0, v54
	v_rcp_f32_e32 v59, v54
	v_lshlrev_b32_e32 v54, 16, v55
	v_and_b32_e32 v55, 0xffff0000, v55
	v_pk_mul_f32 v[56:57], v[58:59], v[56:57]
	s_nop 0
	v_pk_mul_f32 v[50:51], v[56:57], v[50:51]
	v_mul_f32_e32 v56, 0xbfb8aa3b, v54
	v_mul_f32_e32 v57, 0xbfb8aa3b, v55
	v_exp_f32_e32 v56, v56
	v_exp_f32_e32 v57, v57
	v_pk_mul_f32 v[58:59], v[64:65], v[66:67] op_sel_hi:[1,0]
	v_cvt_pk_bf16_f32 v50, v50, v51
	v_add_f32_e32 v56, 1.0, v56
	v_add_f32_e32 v57, 1.0, v57
	v_rcp_f32_e32 v56, v56
	v_rcp_f32_e32 v57, v57
	v_pk_mul_f32 v[52:53], v[52:53], v[58:59]
	v_pk_mul_f32 v[54:55], v[56:57], v[54:55]
	s_nop 0
	v_pk_mul_f32 v[52:53], v[54:55], v[52:53]
	s_nop 0
	v_cvt_pk_bf16_f32 v51, v52, v53
	ds_write_b64 v231, v[50:51]
	ds_read_b64 v[50:51], v232
	s_waitcnt lgkmcnt(0)
	v_lshlrev_b32_e32 v56, 16, v50
	v_and_b32_e32 v57, 0xffff0000, v50
	v_mul_f32_e32 v50, 0xbfb8aa3b, v56
	v_exp_f32_e32 v50, v50
	s_waitcnt vmcnt(11)
	v_mov_b64_e32 v[52:53], v[148:149]
	v_mov_b64_e32 v[54:55], v[150:151]
	v_pk_mul_f32 v[34:35], v[52:53], v[34:35]
	v_add_f32_e32 v50, 1.0, v50
	v_rcp_f32_e32 v58, v50
	v_mul_f32_e32 v50, 0xbfb8aa3b, v57
	v_exp_f32_e32 v50, v50
	v_pk_mul_f32 v[36:37], v[54:55], v[36:37]
	v_add_f32_e32 v50, 1.0, v50
	v_rcp_f32_e32 v59, v50
	v_lshlrev_b32_e32 v50, 16, v51
	v_and_b32_e32 v51, 0xffff0000, v51
	v_pk_mul_f32 v[52:53], v[58:59], v[56:57]
	s_nop 0
	v_pk_mul_f32 v[34:35], v[52:53], v[34:35]
	v_mul_f32_e32 v52, 0xbfb8aa3b, v50
	v_mul_f32_e32 v53, 0xbfb8aa3b, v51
	v_exp_f32_e32 v52, v52
	v_exp_f32_e32 v53, v53
	v_cvt_pk_bf16_f32 v34, v34, v35
	v_add_f32_e32 v52, 1.0, v52
	v_add_f32_e32 v53, 1.0, v53
	v_rcp_f32_e32 v52, v52
	v_rcp_f32_e32 v53, v53
	s_nop 0
	v_pk_mul_f32 v[50:51], v[52:53], v[50:51]
	s_nop 0
	v_pk_mul_f32 v[36:37], v[50:51], v[36:37]
	v_cvt_pk_bf16_f32 v35, v36, v37
	ds_write_b64 v232, v[34:35]
	ds_read_b64 v[34:35], v233
	s_waitcnt lgkmcnt(0)
	v_lshlrev_b32_e32 v36, 16, v34
	v_and_b32_e32 v37, 0xffff0000, v34
	v_mul_f32_e32 v34, 0xbfb8aa3b, v36
	v_exp_f32_e32 v34, v34
	s_waitcnt vmcnt(10)
	v_mov_b64_e32 v[50:51], v[156:157]
	v_mov_b64_e32 v[52:53], v[158:159]
	v_pk_mul_f32 v[38:39], v[50:51], v[38:39]
	v_add_f32_e32 v34, 1.0, v34
	v_rcp_f32_e32 v54, v34
	v_mul_f32_e32 v34, 0xbfb8aa3b, v37
	v_exp_f32_e32 v34, v34
	v_pk_mul_f32 v[40:41], v[52:53], v[40:41]
	v_add_f32_e32 v34, 1.0, v34
	v_rcp_f32_e32 v55, v34
	v_lshlrev_b32_e32 v34, 16, v35
	v_and_b32_e32 v35, 0xffff0000, v35
	v_pk_mul_f32 v[36:37], v[54:55], v[36:37]
	s_nop 0
	v_pk_mul_f32 v[36:37], v[36:37], v[38:39]
	v_mul_f32_e32 v38, 0xbfb8aa3b, v34
	v_mul_f32_e32 v39, 0xbfb8aa3b, v35
	v_exp_f32_e32 v38, v38
	v_exp_f32_e32 v39, v39
	v_cvt_pk_bf16_f32 v36, v36, v37
	v_add_f32_e32 v38, 1.0, v38
	v_add_f32_e32 v39, 1.0, v39
	v_rcp_f32_e32 v38, v38
	v_rcp_f32_e32 v39, v39
	s_nop 0
	v_pk_mul_f32 v[34:35], v[38:39], v[34:35]
	s_nop 0
	v_pk_mul_f32 v[34:35], v[34:35], v[40:41]
	s_nop 0
	v_cvt_pk_bf16_f32 v37, v34, v35
	ds_write_b64 v233, v[36:37]
	ds_read_b64 v[34:35], v234
	s_waitcnt lgkmcnt(0)
	v_lshlrev_b32_e32 v40, 16, v34
	v_and_b32_e32 v41, 0xffff0000, v34
	v_mul_f32_e32 v34, 0xbfb8aa3b, v40
	v_exp_f32_e32 v34, v34
	s_waitcnt vmcnt(9)
	v_mov_b64_e32 v[36:37], v[160:161]
	v_mov_b64_e32 v[38:39], v[162:163]
	v_pk_mul_f32 v[36:37], v[36:37], v[42:43]
	v_add_f32_e32 v34, 1.0, v34
	v_rcp_f32_e32 v50, v34
	v_mul_f32_e32 v34, 0xbfb8aa3b, v41
	v_exp_f32_e32 v34, v34
	v_pk_mul_f32 v[42:43], v[44:45], v[66:67] op_sel_hi:[1,0]
	v_pk_mul_f32 v[44:45], v[46:47], v[66:67] op_sel_hi:[1,0]
	v_pk_mul_f32 v[38:39], v[38:39], v[42:43]
	v_add_f32_e32 v34, 1.0, v34
	v_rcp_f32_e32 v51, v34
	v_lshlrev_b32_e32 v34, 16, v35
	v_and_b32_e32 v35, 0xffff0000, v35
	v_pk_mul_f32 v[40:41], v[50:51], v[40:41]
	s_nop 0
	v_pk_mul_f32 v[36:37], v[40:41], v[36:37]
	v_mul_f32_e32 v40, 0xbfb8aa3b, v34
	v_mul_f32_e32 v41, 0xbfb8aa3b, v35
	v_exp_f32_e32 v40, v40
	v_exp_f32_e32 v41, v41
	v_cvt_pk_bf16_f32 v36, v36, v37
	v_add_f32_e32 v40, 1.0, v40
	v_add_f32_e32 v41, 1.0, v41
	v_rcp_f32_e32 v40, v40
	v_rcp_f32_e32 v41, v41
	s_nop 0
	v_pk_mul_f32 v[34:35], v[40:41], v[34:35]
	s_nop 0
	v_pk_mul_f32 v[34:35], v[34:35], v[38:39]
	ds_read_b64 v[38:39], v235
	v_cvt_pk_bf16_f32 v37, v34, v35
	ds_write_b64 v234, v[36:37]
	s_waitcnt lgkmcnt(1)
	v_lshlrev_b32_e32 v40, 16, v38
	v_and_b32_e32 v41, 0xffff0000, v38
	v_mul_f32_e32 v38, 0xbfb8aa3b, v40
	v_exp_f32_e32 v38, v38
	s_waitcnt vmcnt(8)
	v_mov_b64_e32 v[34:35], v[164:165]
	v_mov_b64_e32 v[36:37], v[166:167]
	v_pk_mul_f32 v[34:35], v[34:35], v[44:45]
	v_add_f32_e32 v38, 1.0, v38
	v_rcp_f32_e32 v42, v38
	v_mul_f32_e32 v38, 0xbfb8aa3b, v41
	v_exp_f32_e32 v38, v38
	s_nop 0
	v_add_f32_e32 v38, 1.0, v38
	v_rcp_f32_e32 v43, v38
	v_lshlrev_b32_e32 v38, 16, v39
	v_and_b32_e32 v39, 0xffff0000, v39
	v_pk_mul_f32 v[40:41], v[42:43], v[40:41]
	s_nop 0
	v_pk_mul_f32 v[34:35], v[40:41], v[34:35]
	v_mul_f32_e32 v40, 0xbfb8aa3b, v38
	v_mul_f32_e32 v41, 0xbfb8aa3b, v39
	v_exp_f32_e32 v40, v40
	v_exp_f32_e32 v41, v41
	v_pk_mul_f32 v[42:43], v[48:49], v[66:67] op_sel_hi:[1,0]
	v_cvt_pk_bf16_f32 v34, v34, v35
	v_add_f32_e32 v40, 1.0, v40
	v_add_f32_e32 v41, 1.0, v41
	v_rcp_f32_e32 v40, v40
	v_rcp_f32_e32 v41, v41
	v_pk_mul_f32 v[36:37], v[36:37], v[42:43]
	v_pk_mul_f32 v[38:39], v[40:41], v[38:39]
	s_nop 0
	v_pk_mul_f32 v[36:37], v[38:39], v[36:37]
	s_nop 0
	v_cvt_pk_bf16_f32 v35, v36, v37
	ds_write_b64 v235, v[34:35]
	ds_read_b64 v[34:35], v236
	s_waitcnt lgkmcnt(0)
	v_lshlrev_b32_e32 v40, 16, v34
	v_and_b32_e32 v41, 0xffff0000, v34
	v_mul_f32_e32 v34, 0xbfb8aa3b, v40
	v_exp_f32_e32 v34, v34
	s_waitcnt vmcnt(7)
	v_mov_b64_e32 v[36:37], v[168:169]
	v_mov_b64_e32 v[38:39], v[170:171]
	v_pk_mul_f32 v[18:19], v[36:37], v[18:19]
	v_add_f32_e32 v34, 1.0, v34
	v_rcp_f32_e32 v42, v34
	v_mul_f32_e32 v34, 0xbfb8aa3b, v41
	v_exp_f32_e32 v34, v34
	v_pk_mul_f32 v[20:21], v[38:39], v[20:21]
	v_add_f32_e32 v34, 1.0, v34
	v_rcp_f32_e32 v43, v34
	v_lshlrev_b32_e32 v34, 16, v35
	v_and_b32_e32 v35, 0xffff0000, v35
	v_pk_mul_f32 v[36:37], v[42:43], v[40:41]
	s_nop 0
	v_pk_mul_f32 v[18:19], v[36:37], v[18:19]
	v_mul_f32_e32 v36, 0xbfb8aa3b, v34
	v_mul_f32_e32 v37, 0xbfb8aa3b, v35
	v_exp_f32_e32 v36, v36
	v_exp_f32_e32 v37, v37
	v_cvt_pk_bf16_f32 v18, v18, v19
	v_add_f32_e32 v36, 1.0, v36
	v_add_f32_e32 v37, 1.0, v37
	v_rcp_f32_e32 v36, v36
	v_rcp_f32_e32 v37, v37
	s_nop 0
	v_pk_mul_f32 v[34:35], v[36:37], v[34:35]
	s_nop 0
	v_pk_mul_f32 v[20:21], v[34:35], v[20:21]
	v_cvt_pk_bf16_f32 v19, v20, v21
	ds_write_b64 v236, v[18:19]
	ds_read_b64 v[18:19], v237
	s_waitcnt lgkmcnt(0)
	v_lshlrev_b32_e32 v20, 16, v18
	v_and_b32_e32 v21, 0xffff0000, v18
	v_mul_f32_e32 v18, 0xbfb8aa3b, v20
	v_exp_f32_e32 v18, v18
	s_waitcnt vmcnt(6)
	v_mov_b64_e32 v[34:35], v[84:85]
	v_mov_b64_e32 v[36:37], v[86:87]
	v_pk_mul_f32 v[22:23], v[34:35], v[22:23]
	v_add_f32_e32 v18, 1.0, v18
	v_rcp_f32_e32 v38, v18
	v_mul_f32_e32 v18, 0xbfb8aa3b, v21
	v_exp_f32_e32 v18, v18
	v_pk_mul_f32 v[24:25], v[36:37], v[24:25]
	v_add_f32_e32 v18, 1.0, v18
	v_rcp_f32_e32 v39, v18
	v_lshlrev_b32_e32 v18, 16, v19
	v_and_b32_e32 v19, 0xffff0000, v19
	v_pk_mul_f32 v[20:21], v[38:39], v[20:21]
	s_nop 0
	v_pk_mul_f32 v[20:21], v[20:21], v[22:23]
	v_mul_f32_e32 v22, 0xbfb8aa3b, v18
	v_mul_f32_e32 v23, 0xbfb8aa3b, v19
	v_exp_f32_e32 v22, v22
	v_exp_f32_e32 v23, v23
	v_cvt_pk_bf16_f32 v20, v20, v21
	v_add_f32_e32 v22, 1.0, v22
	v_add_f32_e32 v23, 1.0, v23
	v_rcp_f32_e32 v22, v22
	v_rcp_f32_e32 v23, v23
	s_nop 0
	v_pk_mul_f32 v[18:19], v[22:23], v[18:19]
	s_nop 0
	v_pk_mul_f32 v[18:19], v[18:19], v[24:25]
	s_nop 0
	v_cvt_pk_bf16_f32 v21, v18, v19
	ds_write_b64 v237, v[20:21]
	ds_read_b64 v[18:19], v238
	s_waitcnt lgkmcnt(0)
	v_lshlrev_b32_e32 v24, 16, v18
	v_and_b32_e32 v25, 0xffff0000, v18
	v_mul_f32_e32 v18, 0xbfb8aa3b, v24
	v_exp_f32_e32 v18, v18
	s_waitcnt vmcnt(5)
	v_mov_b64_e32 v[20:21], v[88:89]
	v_mov_b64_e32 v[22:23], v[90:91]
	v_pk_mul_f32 v[20:21], v[20:21], v[26:27]
	v_add_f32_e32 v18, 1.0, v18
	v_rcp_f32_e32 v34, v18
	v_mul_f32_e32 v18, 0xbfb8aa3b, v25
	v_exp_f32_e32 v18, v18
	v_pk_mul_f32 v[26:27], v[28:29], v[66:67] op_sel_hi:[1,0]
	v_pk_mul_f32 v[28:29], v[30:31], v[66:67] op_sel_hi:[1,0]
	v_pk_mul_f32 v[22:23], v[22:23], v[26:27]
	v_add_f32_e32 v18, 1.0, v18
	v_rcp_f32_e32 v35, v18
	v_lshlrev_b32_e32 v18, 16, v19
	v_and_b32_e32 v19, 0xffff0000, v19
	v_pk_mul_f32 v[24:25], v[34:35], v[24:25]
	s_nop 0
	v_pk_mul_f32 v[20:21], v[24:25], v[20:21]
	v_mul_f32_e32 v24, 0xbfb8aa3b, v18
	v_mul_f32_e32 v25, 0xbfb8aa3b, v19
	v_exp_f32_e32 v24, v24
	v_exp_f32_e32 v25, v25
	v_cvt_pk_bf16_f32 v20, v20, v21
	v_add_f32_e32 v24, 1.0, v24
	v_add_f32_e32 v25, 1.0, v25
	v_rcp_f32_e32 v24, v24
	v_rcp_f32_e32 v25, v25
	s_nop 0
	v_pk_mul_f32 v[18:19], v[24:25], v[18:19]
	s_nop 0
	v_pk_mul_f32 v[18:19], v[18:19], v[22:23]
	ds_read_b64 v[22:23], v239
	v_cvt_pk_bf16_f32 v21, v18, v19
	ds_write_b64 v238, v[20:21]
	s_waitcnt lgkmcnt(1)
	v_lshlrev_b32_e32 v24, 16, v22
	v_and_b32_e32 v25, 0xffff0000, v22
	v_mul_f32_e32 v22, 0xbfb8aa3b, v24
	v_exp_f32_e32 v22, v22
	s_waitcnt vmcnt(4)
	v_mov_b64_e32 v[18:19], v[92:93]
	v_mov_b64_e32 v[20:21], v[94:95]
	v_pk_mul_f32 v[18:19], v[18:19], v[28:29]
	v_add_f32_e32 v22, 1.0, v22
	v_rcp_f32_e32 v26, v22
	v_mul_f32_e32 v22, 0xbfb8aa3b, v25
	v_exp_f32_e32 v22, v22
	s_nop 0
	v_add_f32_e32 v22, 1.0, v22
	v_rcp_f32_e32 v27, v22
	v_lshlrev_b32_e32 v22, 16, v23
	v_and_b32_e32 v23, 0xffff0000, v23
	v_pk_mul_f32 v[24:25], v[26:27], v[24:25]
	s_nop 0
	v_pk_mul_f32 v[18:19], v[24:25], v[18:19]
	v_mul_f32_e32 v24, 0xbfb8aa3b, v22
	v_mul_f32_e32 v25, 0xbfb8aa3b, v23
	v_exp_f32_e32 v24, v24
	v_exp_f32_e32 v25, v25
	v_pk_mul_f32 v[26:27], v[32:33], v[66:67] op_sel_hi:[1,0]
	v_cvt_pk_bf16_f32 v18, v18, v19
	v_add_f32_e32 v24, 1.0, v24
	v_add_f32_e32 v25, 1.0, v25
	v_rcp_f32_e32 v24, v24
	v_rcp_f32_e32 v25, v25
	v_pk_mul_f32 v[20:21], v[20:21], v[26:27]
	v_pk_mul_f32 v[22:23], v[24:25], v[22:23]
	s_nop 0
	v_pk_mul_f32 v[20:21], v[22:23], v[20:21]
	s_nop 0
	v_cvt_pk_bf16_f32 v19, v20, v21
	ds_write_b64 v239, v[18:19]
	ds_read_b64 v[18:19], v240
	s_waitcnt lgkmcnt(0)
	v_lshlrev_b32_e32 v24, 16, v18
	v_and_b32_e32 v25, 0xffff0000, v18
	v_mul_f32_e32 v18, 0xbfb8aa3b, v24
	v_exp_f32_e32 v18, v18
	s_waitcnt vmcnt(3)
	v_mov_b64_e32 v[20:21], v[96:97]
	v_mov_b64_e32 v[22:23], v[98:99]
	v_pk_mul_f32 v[2:3], v[20:21], v[2:3]
	v_add_f32_e32 v18, 1.0, v18
	v_rcp_f32_e32 v26, v18
	v_mul_f32_e32 v18, 0xbfb8aa3b, v25
	v_exp_f32_e32 v18, v18
	v_pk_mul_f32 v[4:5], v[22:23], v[4:5]
	v_add_f32_e32 v18, 1.0, v18
	v_rcp_f32_e32 v27, v18
	v_lshlrev_b32_e32 v18, 16, v19
	v_and_b32_e32 v19, 0xffff0000, v19
	v_pk_mul_f32 v[20:21], v[26:27], v[24:25]
	s_nop 0
	v_pk_mul_f32 v[2:3], v[20:21], v[2:3]
	v_mul_f32_e32 v20, 0xbfb8aa3b, v18
	v_mul_f32_e32 v21, 0xbfb8aa3b, v19
	v_exp_f32_e32 v20, v20
	v_exp_f32_e32 v21, v21
	v_cvt_pk_bf16_f32 v2, v2, v3
	v_add_f32_e32 v20, 1.0, v20
	v_add_f32_e32 v21, 1.0, v21
	v_rcp_f32_e32 v20, v20
	v_rcp_f32_e32 v21, v21
	s_nop 0
	v_pk_mul_f32 v[18:19], v[20:21], v[18:19]
	s_nop 0
	v_pk_mul_f32 v[4:5], v[18:19], v[4:5]
	v_cvt_pk_bf16_f32 v3, v4, v5
	ds_write_b64 v240, v[2:3]
	ds_read_b64 v[2:3], v241
	s_waitcnt lgkmcnt(0)
	v_lshlrev_b32_e32 v4, 16, v2
	v_and_b32_e32 v5, 0xffff0000, v2
	v_mul_f32_e32 v2, 0xbfb8aa3b, v4
	v_exp_f32_e32 v2, v2
	s_waitcnt vmcnt(2)
	v_mov_b64_e32 v[18:19], v[100:101]
	v_mov_b64_e32 v[20:21], v[102:103]
	v_pk_mul_f32 v[6:7], v[18:19], v[6:7]
	v_add_f32_e32 v2, 1.0, v2
	v_rcp_f32_e32 v22, v2
	v_mul_f32_e32 v2, 0xbfb8aa3b, v5
	v_exp_f32_e32 v2, v2
	v_pk_mul_f32 v[8:9], v[20:21], v[8:9]
	v_add_f32_e32 v2, 1.0, v2
	v_rcp_f32_e32 v23, v2
	v_lshlrev_b32_e32 v2, 16, v3
	v_and_b32_e32 v3, 0xffff0000, v3
	v_pk_mul_f32 v[4:5], v[22:23], v[4:5]
	s_nop 0
	v_pk_mul_f32 v[4:5], v[4:5], v[6:7]
	v_mul_f32_e32 v6, 0xbfb8aa3b, v2
	v_mul_f32_e32 v7, 0xbfb8aa3b, v3
	v_exp_f32_e32 v6, v6
	v_exp_f32_e32 v7, v7
	v_cvt_pk_bf16_f32 v4, v4, v5
	v_add_f32_e32 v6, 1.0, v6
	v_add_f32_e32 v7, 1.0, v7
	v_rcp_f32_e32 v6, v6
	v_rcp_f32_e32 v7, v7
	s_nop 0
	v_pk_mul_f32 v[2:3], v[6:7], v[2:3]
	s_nop 0
	v_pk_mul_f32 v[2:3], v[2:3], v[8:9]
	s_nop 0
	v_cvt_pk_bf16_f32 v5, v2, v3
	ds_write_b64 v241, v[4:5]
	ds_read_b64 v[2:3], v242
	s_waitcnt lgkmcnt(0)
	v_lshlrev_b32_e32 v8, 16, v2
	v_and_b32_e32 v9, 0xffff0000, v2
	v_mul_f32_e32 v2, 0xbfb8aa3b, v8
	v_exp_f32_e32 v2, v2
	s_waitcnt vmcnt(1)
	v_mov_b64_e32 v[4:5], v[104:105]
	v_mov_b64_e32 v[6:7], v[106:107]
	v_pk_mul_f32 v[4:5], v[4:5], v[10:11]
	v_add_f32_e32 v2, 1.0, v2
	v_rcp_f32_e32 v18, v2
	v_mul_f32_e32 v2, 0xbfb8aa3b, v9
	v_exp_f32_e32 v2, v2
	v_pk_mul_f32 v[10:11], v[12:13], v[66:67] op_sel_hi:[1,0]
	v_pk_mul_f32 v[12:13], v[14:15], v[66:67] op_sel_hi:[1,0]
	v_pk_mul_f32 v[6:7], v[6:7], v[10:11]
	v_add_f32_e32 v2, 1.0, v2
	v_rcp_f32_e32 v19, v2
	v_lshlrev_b32_e32 v2, 16, v3
	v_and_b32_e32 v3, 0xffff0000, v3
	v_pk_mul_f32 v[8:9], v[18:19], v[8:9]
	s_nop 0
	v_pk_mul_f32 v[4:5], v[4:5], v[8:9]
	v_mul_f32_e32 v8, 0xbfb8aa3b, v2
	v_mul_f32_e32 v9, 0xbfb8aa3b, v3
	v_exp_f32_e32 v8, v8
	v_exp_f32_e32 v9, v9
	v_cvt_pk_bf16_f32 v4, v4, v5
	v_add_f32_e32 v8, 1.0, v8
	v_add_f32_e32 v9, 1.0, v9
	v_rcp_f32_e32 v8, v8
	v_rcp_f32_e32 v9, v9
	s_nop 0
	v_pk_mul_f32 v[2:3], v[8:9], v[2:3]
	s_nop 0
	v_pk_mul_f32 v[2:3], v[6:7], v[2:3]
	ds_read_b64 v[6:7], v243
	v_cvt_pk_bf16_f32 v5, v2, v3
	ds_write_b64 v242, v[4:5]
	s_waitcnt lgkmcnt(1)
	v_lshlrev_b32_e32 v8, 16, v6
	v_and_b32_e32 v9, 0xffff0000, v6
	v_mul_f32_e32 v6, 0xbfb8aa3b, v8
	v_exp_f32_e32 v6, v6
	s_waitcnt vmcnt(0)
	v_mov_b64_e32 v[2:3], v[108:109]
	v_mov_b64_e32 v[4:5], v[110:111]
	v_pk_mul_f32 v[2:3], v[2:3], v[12:13]
	v_add_f32_e32 v6, 1.0, v6
	v_rcp_f32_e32 v10, v6
	v_mul_f32_e32 v6, 0xbfb8aa3b, v9
	v_exp_f32_e32 v6, v6
	s_nop 0
	v_add_f32_e32 v6, 1.0, v6
	v_rcp_f32_e32 v11, v6
	v_lshlrev_b32_e32 v6, 16, v7
	v_and_b32_e32 v7, 0xffff0000, v7
	v_pk_mul_f32 v[8:9], v[10:11], v[8:9]
	s_nop 0
	v_pk_mul_f32 v[2:3], v[2:3], v[8:9]
	v_mul_f32_e32 v8, 0xbfb8aa3b, v6
	v_mul_f32_e32 v9, 0xbfb8aa3b, v7
	v_exp_f32_e32 v8, v8
	v_exp_f32_e32 v9, v9
	v_pk_mul_f32 v[10:11], v[16:17], v[66:67] op_sel_hi:[1,0]
	v_cvt_pk_bf16_f32 v2, v2, v3
	v_add_f32_e32 v8, 1.0, v8
	v_add_f32_e32 v9, 1.0, v9
	v_rcp_f32_e32 v8, v8
	v_rcp_f32_e32 v9, v9
	v_pk_mul_f32 v[4:5], v[4:5], v[10:11]
	v_pk_mul_f32 v[6:7], v[8:9], v[6:7]
	s_nop 0
	v_pk_mul_f32 v[4:5], v[4:5], v[6:7]
	v_lshl_add_u64 v[6:7], v[174:175], 0, s[4:5]
	v_cvt_pk_bf16_f32 v3, v4, v5
	ds_write_b64 v243, v[2:3]
	ds_read2_b64 v[2:5], v228 offset1:1
	v_lshl_add_u64 v[8:9], v[6:7], 0, v[190:191]
	s_mov_b64 s[4:5], 0
	s_waitcnt lgkmcnt(0)
	global_store_dwordx4 v[8:9], v[2:5], off
	ds_read2_b64 v[2:5], v229 offset1:1
	v_lshl_add_u64 v[8:9], v[6:7], 0, v[192:193]
	s_waitcnt lgkmcnt(0)
	global_store_dwordx4 v[8:9], v[2:5], off
	ds_read2_b64 v[2:5], v229 offset0:132 offset1:133
	v_lshl_add_u64 v[8:9], v[6:7], 0, v[194:195]
	s_waitcnt lgkmcnt(0)
	global_store_dwordx4 v[8:9], v[2:5], off
	ds_read2_b64 v[2:5], v67 offset1:1
	v_lshl_add_u64 v[8:9], v[6:7], 0, v[196:197]
	s_waitcnt lgkmcnt(0)
	global_store_dwordx4 v[8:9], v[2:5], off
	ds_read2_b64 v[2:5], v68 offset1:1
	v_lshl_add_u64 v[8:9], v[6:7], 0, v[198:199]
	s_waitcnt lgkmcnt(0)
	global_store_dwordx4 v[8:9], v[2:5], off
	ds_read2_b64 v[2:5], v70 offset1:1
	v_lshl_add_u64 v[8:9], v[6:7], 0, v[200:201]
	s_waitcnt lgkmcnt(0)
	global_store_dwordx4 v[8:9], v[2:5], off
	ds_read2_b64 v[2:5], v71 offset1:1
	v_lshl_add_u64 v[8:9], v[6:7], 0, v[202:203]
	v_lshl_add_u64 v[6:7], v[6:7], 0, v[204:205]
	s_waitcnt lgkmcnt(0)
	global_store_dwordx4 v[8:9], v[2:5], off
	ds_read2_b64 v[2:5], v69 offset1:1
	s_waitcnt lgkmcnt(0)
	global_store_dwordx4 v[6:7], v[2:5], off
	s_cbranch_vccz .LBB0_641
